# phase-0 weight conversion loop: the wait before the LDS writes no longer waits for the previous tile's output store
# speedup vs baseline: 1.0039x; 1.0039x over previous
; #define LAS __attribute__((address_space(3)))
; __device__ __forceinline__ int opaque_tid() { int t = threadIdx.x; asm volatile("" : "+v"(t)); return t; }
; __device__ __forceinline__ void conv_range(const Params& p, LAS unsigned char* lds, int t0, int t1, int rank, int nranks) {
;     LAS float* tile = (LAS float*)lds;
;     const int tid = opaque_tid(); const int r = tid >> 4, c4 = (tid & 15) * 4, n = tid >> 3, k8 = (tid & 7) * 8;
;     int i = t0 + rank; f32x4 v0 = ZERO4, v1 = ZERO4;
;     if (i < t1) { const TDesc d = tile_desc(p, i); v0 = *(const f32x4*)(d.src + (size_t)r * d.ld_src + c4); v1 = *(const f32x4*)(d.src + (size_t)(r + 32) * d.ld_src + c4); }
.LBB0_682:
	s_mov_b32 s99, 0
	v_ashrrev_i32_e32 v0, 4, v13
	v_lshlrev_b32_e32 v1, 2, v13
	v_add_u32_e32 v12, 32, v0
	v_and_b32_e32 v16, 60, v1
	v_ashrrev_i32_e32 v1, 31, v12
	v_mul_lo_u32 v3, s34, v1
	v_mul_lo_u32 v6, s35, v12
	v_mad_u64_u32 v[4:5], s[0:1], s34, v12, 0
	v_add3_u32 v5, v5, v3, v6
	v_ashrrev_i32_e32 v3, 31, v0
	v_mul_lo_u32 v8, s34, v3
	v_mul_lo_u32 v9, s35, v0
	v_mad_u64_u32 v[6:7], s[0:1], s34, v0, 0
	v_add3_u32 v7, v7, v8, v9
	v_lshl_add_u64 v[4:5], v[4:5], 2, s[30:31]
	v_lshlrev_b32_e32 v18, 2, v16
	v_mov_b32_e32 v19, v2
	v_lshl_add_u64 v[6:7], v[6:7], 2, s[30:31]
	v_lshl_add_u64 v[4:5], v[4:5], 0, v[18:19]
	v_lshl_add_u64 v[6:7], v[6:7], 0, v[18:19]
	global_load_dwordx4 v[8:11], v[4:5], off
	s_nop 0
	global_load_dwordx4 v[4:7], v[6:7], off
	v_ashrrev_i32_e32 v14, 3, v13
	v_lshlrev_b32_e32 v13, 3, v13
	v_and_b32_e32 v22, 56, v13
	s_movk_i32 s0, 0x104
	v_add_u32_e32 v15, 0, v18
	v_mul_lo_u32 v17, v0, s0
	v_lshl_add_u32 v18, v14, 2, 0
	v_mul_u32_u24_e32 v19, 0x104, v22
	s_add_i32 s0, s68, 0xfffff740
	s_add_i32 s1, s41, s68
	v_ashrrev_i32_e32 v13, 31, v14
	s_lshl_b32 s89, s41, 6
	s_lshl_b32 s86, s68, 6
	s_lshl_b32 s90, s41, 2
	s_lshl_b32 s92, s68, 2
	s_lshl_b32 s91, s41, 17
	s_lshl_b32 s42, s68, 17
	v_writelane_b32 v255, s0, 30
	s_add_i32 s0, s1, 0xf740
	s_lshl_b32 s1, s1, 14
	s_lshl_b32 s84, s68, 14
	s_add_i32 s94, s41, 0xf740
	s_lshl_b32 s40, s41, 4
	s_lshl_b32 s43, s68, 4
	v_add_u32_e32 v15, v15, v17
	v_lshlrev_b32_e32 v16, 2, v16
	v_add_u32_e32 v20, v18, v19
	v_lshlrev_b32_e32 v18, 1, v22
	s_branch .LBB0_685

; #define LAS __attribute__((address_space(3)))
; __device__ __forceinline__ void lds_barrier() { asm volatile("s_waitcnt lgkmcnt(0)" ::: "memory"); __builtin_amdgcn_s_barrier(); asm volatile("" ::: "memory"); }
; __device__ __forceinline__ TDesc tile_desc(const Params& p, int i) {
;     TDesc d; const int l = i / 4352; int r = i - l * 4352;
;     if (r < 1728) { const int kt = r / 108, nt = r - kt * 108;
;         d.src = p.w_in + (size_t)l * 1024 * 6912 + (size_t)(kt * 64) * 6912 + nt * 64; d.ld_src = 6912; d.dst = p.wt_in + (size_t)l * 6912 * 1024 + (size_t)(nt * 64) * 1024 + kt * 64; d.ld_dst = 1024; return d; }
; __device__ __forceinline__ void conv_range(const Params& p, LAS unsigned char* lds, int t0, int t1, int rank, int nranks) {
;     ...
;     for (; i < t1; i += nranks) {
;         const TDesc d = tile_desc(p, i);
;         lds_barrier();
;         { LAS float* tp = tile + r * 65 + c4; tp[0] = v0[0]; tp[1] = v0[1]; tp[2] = v0[2]; tp[3] = v0[3]; tp += 32 * 65; tp[0] = v1[0]; tp[1] = v1[1]; tp[2] = v1[2]; tp[3] = v1[3]; }
;         if (i + nranks < t1) { const TDesc dn = tile_desc(p, i + nranks); v0 = *(const f32x4*)(dn.src + (size_t)r * dn.ld_src + c4); v1 = *(const f32x4*)(dn.src + (size_t)(r + 32) * dn.ld_src + c4); }
.LBB0_701:
	s_add_i32 s87, s41, s68
	s_waitcnt lgkmcnt(0)
	s_barrier
	s_cmpk_gt_i32 s87, 0x10ff
	v_add_u32_e32 v17, 0x2080, v15
	s_cselect_b64 s[34:35], -1, 0
	s_cmp_lg_u32 s99, 0
	s_cbranch_scc1 .Lconv0_w1
	s_waitcnt vmcnt(0)
.Lconv0_w1:
	s_waitcnt vmcnt(1)
	s_mov_b32 s99, 1
	ds_write2_b32 v15, v4, v5 offset1:1
	ds_write2_b32 v15, v6, v7 offset0:2 offset1:3
	ds_write2_b32 v17, v8, v9 offset1:1
	v_add_u32_e32 v17, 0x2088, v15
	s_and_b64 vcc, exec, s[34:35]
	ds_write2_b32 v17, v10, v11 offset1:1
	s_cbranch_vccnz .LBB0_684
	s_mul_hi_i32 s36, s87, 0x78787879
	s_lshr_b32 s37, s36, 31
	s_ashr_i32 s36, s36, 11
	s_add_i32 s36, s36, s37
	s_mul_i32 s37, s36, 0xffffef00
	s_add_i32 s69, s87, s37
	s_cmpk_gt_i32 s69, 0x6bf
	s_mov_b64 s[74:75], -1
	s_cbranch_scc0 .LBB0_716
	s_cmpk_gt_u32 s69, 0x7bf
	s_cbranch_scc0 .LBB0_713
	s_cmpk_gt_u32 s69, 0x8bf
	s_cbranch_scc0 .LBB0_710
	s_cmpk_gt_u32 s69, 0xe3f
	s_mov_b64 s[72:73], -1
	s_cbranch_scc0 .LBB0_707
	s_mul_i32 s70, s36, 0xb00000
	v_readlane_b32 s71, v255, 26
	s_mul_hi_i32 s37, s36, 0xb00000
	s_add_u32 s72, s71, s70
	v_readlane_b32 s70, v255, 27
	s_addc_u32 s37, s70, s37
	s_mul_i32 s70, s36, 0xffffbc00
	s_add_i32 s71, s92, s90
	s_add_i32 s70, s71, s70
	s_andn2_b32 s70, s70, 63
	s_mov_b32 s71, s13
	s_addk_i32 s70, 0xc700
	s_lshl_b64 s[70:71], s[70:71], 12
	s_add_u32 s70, s72, s70
	s_addc_u32 s37, s37, s71
	s_add_i32 s71, s86, s89
	s_and_b32 s71, s71, 0x3c0
	s_lshl_b32 s71, s71, 2
	s_add_u32 s70, s70, s71
	s_addc_u32 s71, s37, 0
	s_mov_b64 s[72:73], 0
